# defer own-group wait of DN->PP seams to after PP step (PP independent of DN output)
# baseline (speedup 1.0000x reference)
.Lg5_BB0_991:
	s_or_b64 exec, exec, s[6:7]
	s_and_b32 s4, s81, 7
	s_lshl_b32 s4, s4, 3
	s_bfe_u32 s5, s81, 0x30003
	s_add_i32 s4, s4, s5
	s_lshr_b32 s12, s4, 2
	s_mov_b32 s13, 1
	s_mov_b32 s14, -1
	v_mov_b32_e32 v1, 0
	s_mov_b32 s9, 16
	s_mov_b32 s8, 0

.LBB0_1287:
	s_waitcnt vmcnt(0) lgkmcnt(0)
	s_mov_b64 s[0:1], exec
	v_readlane_b32 s2, v249, 10
	v_readlane_b32 s3, v249, 11
	s_and_b64 s[2:3], s[0:1], s[2:3]
	s_mov_b64 exec, s[2:3]
	s_cbranch_execz .Lq5_done
	s_and_b32 s4, s81, 7
	s_lshl_b32 s4, s4, 3
	s_bfe_u32 s5, s81, 0x30003
	s_add_i32 s4, s4, s5
	s_mov_b32 s12, s4
	s_mov_b32 s13, 1
	s_lshr_b32 s14, s4, 2
	s_add_i32 s14, s14, 48
	v_mov_b32_e32 v1, 0
	s_mov_b32 s9, 16
	s_mov_b32 s8, 0

.Lq5_done:
	s_or_b64 exec, exec, s[0:1]
	s_barrier
.LBB0_1288:
	v_readlane_b32 s2, v249, 4
	v_readlane_b32 s3, v249, 5
	s_cmp_lt_i32 s2, 8
	s_cselect_b64 s[0:1], -1, 0
	s_cmp_gt_i32 s3, 7
	s_cselect_b64 s[2:3], -1, 0
	s_and_b64 s[0:1], s[0:1], s[2:3]
	s_andn2_b64 vcc, exec, s[0:1]
	s_cbranch_vccnz .LBB0_1465
	s_mov_b64 s[2:3], s[82:83]
	v_mov_b32_e32 v1, v178
	s_cmpk_lt_i32 s81, 0x100
	s_cselect_b64 s[0:1], -1, 0
	s_cmpk_gt_i32 s81, 0xff
	v_readfirstlane_b32 s6, v1
	s_cbranch_scc1 .LBB0_1295
	s_ashr_i32 s4, s81, 31
	s_lshr_b32 s4, s4, 29
	s_add_i32 s7, s81, s4
	s_and_b32 s4, s7, -8
	s_sub_i32 s8, s81, s4
	s_cmp_gt_i32 s8, -1
	s_cbranch_scc0 .LBB0_1292
	s_lshl_b32 s9, s8, 5
	s_cbranch_execz .LBB0_1293
	s_branch .LBB0_1294

.Lg12_BB0_991:
	s_or_b64 exec, exec, s[6:7]
	s_and_b32 s4, s81, 7
	s_lshl_b32 s4, s4, 3
	s_bfe_u32 s5, s81, 0x30003
	s_add_i32 s4, s4, s5
	s_lshr_b32 s12, s4, 2
	s_mov_b32 s13, 1
	s_mov_b32 s14, -1
	v_mov_b32_e32 v1, 0
	s_mov_b32 s9, 28
	s_mov_b32 s8, 0

.LBB0_2423:
	s_waitcnt vmcnt(0) lgkmcnt(0)
	s_mov_b64 s[0:1], exec
	v_readlane_b32 s2, v249, 10
	v_readlane_b32 s3, v249, 11
	s_and_b64 s[2:3], s[0:1], s[2:3]
	s_mov_b64 exec, s[2:3]
	s_cbranch_execz .Lq12_done
	s_and_b32 s4, s81, 7
	s_lshl_b32 s4, s4, 3
	s_bfe_u32 s5, s81, 0x30003
	s_add_i32 s4, s4, s5
	s_mov_b32 s12, s4
	s_mov_b32 s13, 1
	s_mov_b32 s14, -1
	v_mov_b32_e32 v1, 0
	s_mov_b32 s9, 28
	s_mov_b32 s8, 0

.Lq12_done:
	s_or_b64 exec, exec, s[0:1]
	s_barrier
.LBB0_2424:
	v_readlane_b32 s2, v249, 4
	v_readlane_b32 s3, v249, 5
	s_cmp_lt_i32 s2, 15
	s_cselect_b64 s[0:1], -1, 0
	s_cmp_gt_i32 s3, 14
	s_cselect_b64 s[2:3], -1, 0
	s_and_b64 s[0:1], s[0:1], s[2:3]
	s_andn2_b64 vcc, exec, s[0:1]
	s_cbranch_vccnz .LBB0_2450
	s_cmpk_gt_i32 s81, 0xff
	v_readfirstlane_b32 s10, v178
	s_cbranch_scc1 .LBB0_2449
	s_ashr_i32 s33, s81, 31
	s_lshr_b32 s0, s33, 29
	s_add_i32 s3, s81, s0
	s_and_b32 s0, s3, -8
	s_sub_i32 s2, s81, s0
	s_cmp_gt_i32 s2, -1
	s_cbranch_scc0 .LBB0_2428
	s_lshl_b32 s4, s2, 5
	s_ashr_i32 s0, s3, 3
	s_cbranch_execz .LBB0_2429
	s_branch .LBB0_2430
